# attention item->(pr,h,b) remap: all 64 groups of an XCD share the K/V streams of 4 (b,h) pairs (attnA) / one (b,kv-group) (attnC) for L2 reuse
# speedup vs baseline: 1.0216x; 1.0216x over previous
.LBB0_1041:
	s_or_b64 exec, exec, s[0:1]
	v_mov_b32_e32 v0, v205
	s_waitcnt lgkmcnt(0)
	s_barrier
	v_readlane_b32 s0, v250, 1
	v_and_b32_e32 v2, 63, v0
	v_lshlrev_b32_e32 v2, 2, v2
	global_load_dword v3, v2, s[78:79]
	global_load_dword v4, v2, s[78:79] offset:256
	v_readlane_b32 s1, v250, 2
	v_xor_b32_e32 v5, 32, v214
	v_readlane_b32 s2, v250, 3
	v_readlane_b32 s3, v250, 4
	v_readlane_b32 s4, v250, 5
	v_readlane_b32 s5, v250, 6
	v_readlane_b32 s6, v250, 7
	v_readlane_b32 s7, v250, 8
	s_waitcnt vmcnt(0)
	v_max_f32_e64 v3, |v3|, |v3|
	v_max_f32_e64 v4, |v4|, |v4|
	v_max_f32_e32 v3, v3, v4
	global_load_dword v4, v2, s[0:1]
	s_nop 0
	global_load_dword v2, v2, s[0:1] offset:256
	v_readfirstlane_b32 s0, v204
	s_lshr_b32 s0, s0, 8
	v_readlane_b32 s1, v250, 43
	s_add_i32 s14, s0, s1
	s_and_b32 s0, s14, 1
	s_bfe_u32 s1, s14, 0x30004
	s_lshl_b32 s1, s1, 1
	s_or_b32 s0, s0, s1
	s_bfe_u32 s1, s14, 0x10001
	s_lshl_b32 s1, s1, 6
	s_or_b32 s0, s0, s1
	s_bfe_u32 s1, s14, 0x20007
	s_lshl_b32 s1, s1, 4
	s_or_b32 s0, s0, s1
	s_bfe_u32 s1, s14, 0x20002
	s_lshl_b32 s1, s1, 7
	s_or_b32 s14, s0, s1
	s_cmpk_lt_i32 s14, 0x200
	s_waitcnt vmcnt(1)
	v_max_f32_e64 v4, |v4|, |v4|
	s_waitcnt vmcnt(0)
	v_max_f32_e64 v2, |v2|, |v2|
	v_max_f32_e32 v2, v4, v2
	v_and_b32_e32 v4, 64, v214
	v_add_u32_e32 v4, 64, v4
	v_cmp_lt_i32_e32 vcc, v5, v4
	s_nop 1
	v_cndmask_b32_e32 v5, v214, v5, vcc
	v_lshlrev_b32_e32 v170, 2, v5
	ds_bpermute_b32 v5, v170, v3
	s_waitcnt lgkmcnt(0)
	v_max_f32_e32 v5, v5, v5
	v_max_f32_e32 v3, v3, v5
	ds_bpermute_b32 v5, v170, v2
	s_waitcnt lgkmcnt(0)
	v_max_f32_e32 v5, v5, v5
	v_max_f32_e32 v2, v2, v5
	v_xor_b32_e32 v5, 16, v214
	v_cmp_lt_i32_e32 vcc, v5, v4
	s_nop 1
	v_cndmask_b32_e32 v5, v214, v5, vcc
	v_lshlrev_b32_e32 v5, 2, v5
	ds_bpermute_b32 v6, v5, v3
	ds_bpermute_b32 v5, v5, v2
	s_waitcnt lgkmcnt(1)
	v_max_f32_e32 v6, v6, v6
	s_waitcnt lgkmcnt(0)
	v_max_f32_e32 v5, v5, v5
	v_max_f32_e32 v2, v2, v5
	v_xor_b32_e32 v5, 8, v214
	v_cmp_lt_i32_e32 vcc, v5, v4
	v_max_f32_e32 v3, v3, v6
	s_nop 0
	v_cndmask_b32_e32 v5, v214, v5, vcc
	v_lshlrev_b32_e32 v174, 2, v5
	ds_bpermute_b32 v5, v174, v3
	s_waitcnt lgkmcnt(0)
	v_max_f32_e32 v5, v5, v5
	v_max_f32_e32 v3, v3, v5
	ds_bpermute_b32 v5, v174, v2
	s_waitcnt lgkmcnt(0)
	v_max_f32_e32 v5, v5, v5
	v_max_f32_e32 v2, v2, v5
	v_xor_b32_e32 v5, 4, v214
	v_cmp_lt_i32_e32 vcc, v5, v4
	s_nop 1
	v_cndmask_b32_e32 v5, v214, v5, vcc
	v_lshlrev_b32_e32 v175, 2, v5
	ds_bpermute_b32 v5, v175, v3
	s_waitcnt lgkmcnt(0)
	v_max_f32_e32 v5, v5, v5
	v_max_f32_e32 v3, v3, v5
	ds_bpermute_b32 v5, v175, v2
	s_waitcnt lgkmcnt(0)
	v_max_f32_e32 v5, v5, v5
	v_max_f32_e32 v5, v2, v5
	v_xor_b32_e32 v2, 2, v214
	v_cmp_lt_i32_e32 vcc, v2, v4
	s_nop 1
	v_cndmask_b32_e32 v2, v214, v2, vcc
	v_lshlrev_b32_e32 v176, 2, v2
	ds_bpermute_b32 v2, v176, v3
	s_waitcnt lgkmcnt(0)
	v_max_f32_e32 v2, v2, v2
	v_max_f32_e32 v2, v3, v2
	ds_bpermute_b32 v3, v176, v5
	s_waitcnt lgkmcnt(0)
	v_max_f32_e32 v3, v3, v3
	v_max_f32_e32 v3, v5, v3
	v_xor_b32_e32 v5, 1, v214
	v_cmp_lt_i32_e32 vcc, v5, v4
	s_nop 1
	v_cndmask_b32_e32 v4, v214, v5, vcc
	v_lshlrev_b32_e32 v177, 2, v4
	ds_bpermute_b32 v4, v177, v2
	ds_bpermute_b32 v5, v177, v3
	s_cbranch_scc0 .LBB0_1067
	s_waitcnt lgkmcnt(1)
	v_max_f32_e32 v4, v4, v4
	v_max_f32_e32 v2, v2, v2
	s_waitcnt lgkmcnt(0)
	v_max_f32_e32 v5, v5, v5
	v_max_f32_e32 v3, v3, v3
	v_max_f32_e32 v2, v2, v4
	v_max_f32_e32 v3, v3, v5
	v_mul_f32_e32 v2, 0x413504f3, v2
	v_mul_f32_e32 v2, v3, v2
	v_mul_f32_e32 v2, 0x3fb8aa3b, v2
	v_mul_f32_e32 v16, 0xbf8147ae, v2
	v_ashrrev_i32_e32 v2, 1, v0
	s_movk_i32 s0, 0xffe0
	v_bfi_b32 v171, s0, v2, v0
	v_lshrrev_b32_e32 v0, 2, v0
	v_readlane_b32 s0, v252, 31
	v_and_b32_e32 v0, 8, v0
	v_readlane_b32 s1, v252, 32
	v_mov_b32_e32 v17, v16
	v_mov_b32_e32 v18, v16
	v_mov_b32_e32 v19, v16
	v_mov_b32_e32 v20, v16
	v_mov_b32_e32 v21, v16
	v_mov_b32_e32 v22, v16
	v_mov_b32_e32 v23, v16
	v_mov_b32_e32 v24, v16
	v_mov_b32_e32 v25, v16
	v_mov_b32_e32 v26, v16
	v_mov_b32_e32 v27, v16
	v_mov_b32_e32 v28, v16
	v_mov_b32_e32 v29, v16
	v_mov_b32_e32 v30, v16
	v_mov_b32_e32 v31, v16
	v_lshl_add_u64 v[160:161], s[0:1], 0, v[0:1]

.LBB0_1346:
	s_or_b64 exec, exec, s[0:1]
	v_mov_b32_e32 v0, v205
	s_waitcnt lgkmcnt(0)
	s_barrier
	v_readlane_b32 s0, v250, 19
	v_and_or_b32 v2, v0, 63, s20
	v_lshlrev_b32_e32 v6, 2, v2
	v_readlane_b32 s12, v250, 31
	v_readlane_b32 s13, v250, 32
	v_readlane_b32 s14, v250, 33
	v_readlane_b32 s15, v250, 34
	s_nop 2
	global_load_dword v2, v6, s[12:13]
	s_nop 0
	global_load_dword v3, v6, s[14:15]
	global_load_dword v5, v6, s[64:65]
	global_load_dword v7, v6, s[66:67]
	v_and_b32_e32 v9, 64, v214
	v_add_u32_e32 v9, 64, v9
	v_xor_b32_e32 v10, 32, v214
	v_cmp_lt_i32_e32 vcc, v10, v9
	v_readlane_b32 s8, v250, 27
	v_readlane_b32 s9, v250, 28
	v_cndmask_b32_e32 v10, v214, v10, vcc
	v_lshlrev_b32_e32 v192, 2, v10
	v_readlane_b32 s10, v250, 29
	v_readlane_b32 s11, v250, 30
	v_readlane_b32 s1, v250, 20
	v_readfirstlane_b32 s0, v204
	s_lshr_b32 s0, s0, 8
	v_readlane_b32 s1, v250, 43
	s_add_i32 s26, s0, s1
	s_and_b32 s0, s26, 1
	s_bfe_u32 s1, s26, 0x30004
	s_lshl_b32 s1, s1, 1
	s_or_b32 s0, s0, s1
	s_bfe_u32 s1, s26, 0x10001
	s_lshl_b32 s1, s1, 6
	s_or_b32 s0, s0, s1
	s_bfe_u32 s1, s26, 0x20007
	s_lshl_b32 s1, s1, 4
	s_or_b32 s0, s0, s1
	s_bfe_u32 s1, s26, 0x20002
	s_lshl_b32 s1, s1, 7
	s_or_b32 s26, s0, s1
	s_cmpk_lt_i32 s26, 0x200
	v_readlane_b32 s2, v250, 21
	v_readlane_b32 s3, v250, 22
	v_readlane_b32 s4, v250, 23
	v_readlane_b32 s5, v250, 24
	v_readlane_b32 s6, v250, 25
	v_readlane_b32 s7, v250, 26
	s_waitcnt vmcnt(0)
	v_mul_f32_e32 v4, v2, v3
	ds_bpermute_b32 v4, v192, v4
	v_mul_f32_e32 v8, v5, v7
	s_waitcnt lgkmcnt(0)
	v_fmac_f32_e32 v4, v2, v3
	ds_bpermute_b32 v2, v192, v8
	global_load_dword v8, v6, s[8:9]
	v_xor_b32_e32 v3, 16, v214
	global_load_dword v6, v6, s[10:11]
	v_cmp_lt_i32_e32 vcc, v3, v9
	s_waitcnt lgkmcnt(0)
	v_fmac_f32_e32 v2, v5, v7
	s_waitcnt vmcnt(0)
	v_and_b32_e32 v10, 0x7fffffff, v6
	v_cndmask_b32_e32 v3, v214, v3, vcc
	v_lshlrev_b32_e32 v7, 2, v3
	ds_bpermute_b32 v3, v7, v4
	v_max_f32_e64 v6, |v6|, |v6|
	s_waitcnt lgkmcnt(0)
	v_add_f32_e32 v3, v4, v3
	ds_bpermute_b32 v4, v7, v2
	s_waitcnt lgkmcnt(0)
	v_add_f32_e32 v2, v2, v4
	v_xor_b32_e32 v4, 8, v214
	v_cmp_lt_i32_e32 vcc, v4, v9
	s_nop 1
	v_cndmask_b32_e32 v4, v214, v4, vcc
	v_lshlrev_b32_e32 v188, 2, v4
	ds_bpermute_b32 v4, v188, v3
	s_waitcnt lgkmcnt(0)
	v_add_f32_e32 v3, v3, v4
	ds_bpermute_b32 v4, v188, v2
	s_waitcnt lgkmcnt(0)
	v_add_f32_e32 v2, v2, v4
	v_xor_b32_e32 v4, 4, v214
	v_cmp_lt_i32_e32 vcc, v4, v9
	s_nop 1
	v_cndmask_b32_e32 v4, v214, v4, vcc
	v_lshlrev_b32_e32 v189, 2, v4
	ds_bpermute_b32 v4, v189, v3
	s_waitcnt lgkmcnt(0)
	v_add_f32_e32 v3, v3, v4
	ds_bpermute_b32 v4, v189, v2
	s_waitcnt lgkmcnt(0)
	v_add_f32_e32 v2, v2, v4
	v_xor_b32_e32 v4, 2, v214
	v_cmp_lt_i32_e32 vcc, v4, v9
	s_nop 1
	v_cndmask_b32_e32 v4, v214, v4, vcc
	v_lshlrev_b32_e32 v190, 2, v4
	ds_bpermute_b32 v4, v190, v3
	s_waitcnt lgkmcnt(0)
	v_add_f32_e32 v4, v3, v4
	ds_bpermute_b32 v3, v190, v2
	s_waitcnt lgkmcnt(0)
	v_add_f32_e32 v2, v2, v3
	v_xor_b32_e32 v3, 1, v214
	v_cmp_lt_i32_e32 vcc, v3, v9
	v_and_b32_e32 v9, 0x7fffffff, v8
	ds_bpermute_b32 v9, v192, v9
	v_max_f32_e64 v8, |v8|, |v8|
	v_cndmask_b32_e32 v3, v214, v3, vcc
	v_lshlrev_b32_e32 v191, 2, v3
	ds_bpermute_b32 v5, v191, v4
	s_waitcnt lgkmcnt(1)
	v_max_f32_e32 v9, v9, v9
	v_max_f32_e32 v8, v8, v9
	ds_bpermute_b32 v9, v192, v10
	ds_bpermute_b32 v3, v191, v2
	s_waitcnt lgkmcnt(1)
	v_max_f32_e32 v9, v9, v9
	v_max_f32_e32 v6, v6, v9
	ds_bpermute_b32 v9, v7, v8
	ds_bpermute_b32 v7, v7, v6
	s_waitcnt lgkmcnt(1)
	v_max_f32_e32 v9, v9, v9
	v_max_f32_e32 v8, v8, v9
	s_waitcnt lgkmcnt(0)
	v_max_f32_e32 v7, v7, v7
	v_max_f32_e32 v6, v6, v7
	ds_bpermute_b32 v7, v188, v8
	s_waitcnt lgkmcnt(0)
	v_max_f32_e32 v7, v7, v7
	v_max_f32_e32 v7, v8, v7
	ds_bpermute_b32 v8, v188, v6
	s_waitcnt lgkmcnt(0)
	v_max_f32_e32 v8, v8, v8
	v_max_f32_e32 v6, v6, v8
	ds_bpermute_b32 v8, v189, v7
	s_waitcnt lgkmcnt(0)
	v_max_f32_e32 v8, v8, v8
	v_max_f32_e32 v7, v7, v8
	ds_bpermute_b32 v8, v189, v6
	s_waitcnt lgkmcnt(0)
	v_max_f32_e32 v8, v8, v8
	v_max_f32_e32 v8, v6, v8
	ds_bpermute_b32 v6, v190, v7
	s_waitcnt lgkmcnt(0)
	v_max_f32_e32 v6, v6, v6
	v_max_f32_e32 v6, v7, v6
	ds_bpermute_b32 v7, v190, v8
	s_waitcnt lgkmcnt(0)
	v_max_f32_e32 v7, v7, v7
	v_max_f32_e32 v8, v8, v7
	ds_bpermute_b32 v7, v191, v6
	ds_bpermute_b32 v9, v191, v8
	s_cbranch_scc0 .LBB0_1435
	v_add_f32_e32 v4, v4, v5
	v_mul_f32_e32 v5, 0x3fb8aa3b, v4
	s_mov_b32 s0, 0x3fb8aa3b
	v_fma_f32 v10, v4, s0, -v5
	v_rndne_f32_e32 v11, v5
	v_fmac_f32_e32 v10, 0x32a5705f, v4
	v_sub_f32_e32 v5, v5, v11
	v_add_f32_e32 v5, v5, v10
	v_exp_f32_e32 v5, v5
	v_cvt_i32_f32_e32 v10, v11
	v_readlane_b32 s2, v251, 48
	v_add_f32_e32 v2, v2, v3
	v_mov_b32_e32 v11, 0x3f0e59d5
	v_mov_b32_e32 v12, 0x3e4ccccd
	v_readlane_b32 s3, v251, 49
	v_ldexp_f32 v3, v5, v10
	v_mul_f32_e32 v5, 0x3fb8aa3b, v2
	v_cndmask_b32_e64 v11, v11, v12, s[2:3]
	v_fma_f32 v10, v2, s0, -v5
	v_rndne_f32_e32 v12, v5
	v_fmac_f32_e32 v10, 0x32a5705f, v2
	v_sub_f32_e32 v5, v5, v12
	v_add_f32_e32 v5, v5, v10
	v_exp_f32_e32 v5, v5
	v_cvt_i32_f32_e32 v10, v12
	s_mov_b32 s0, 0xc2ce8ed0
	v_cmp_ngt_f32_e32 vcc, s0, v4
	s_mov_b32 s1, 0x42b17218
	v_mov_b32_e32 v12, 0x7f800000
	v_cndmask_b32_e32 v3, 0, v3, vcc
	v_cmp_nlt_f32_e32 vcc, s1, v4
	v_ldexp_f32 v4, v5, v10
	s_movk_i32 s2, 0xffe0
	v_cndmask_b32_e32 v3, v12, v3, vcc
	v_cmp_ngt_f32_e32 vcc, s0, v2
	v_sub_f32_e32 v193, 1.0, v11
	s_nop 0
	v_cndmask_b32_e32 v4, 0, v4, vcc
	v_cmp_nlt_f32_e32 vcc, s1, v2
	v_readlane_b32 s0, v251, 45
	v_readlane_b32 s1, v251, 46
	v_cndmask_b32_e32 v2, v12, v4, vcc
	v_sub_f32_e32 v2, v3, v2
	v_add_f32_e32 v176, v11, v2
	s_waitcnt lgkmcnt(0)
	v_max_f32_e32 v2, v9, v9
	v_max_f32_e32 v3, v8, v8
	v_max_f32_e32 v2, v3, v2
	v_max_f32_e32 v3, v7, v7
	v_max_f32_e32 v4, v6, v6
	v_max_f32_e32 v3, v4, v3
	v_mul_f32_e32 v3, 0x41000000, v3
	v_mul_f32_e32 v2, v2, v3
	v_mul_f32_e32 v2, 0x3fb8aa3b, v2
	s_and_b64 s[0:1], s[0:1], exec
	v_mul_f32_e32 v16, 0xbf8147ae, v2
	v_ashrrev_i32_e32 v2, 1, v0
	s_cselect_b32 s0, 0x200, 0
	v_bfi_b32 v194, s2, v2, v0
	v_lshrrev_b32_e32 v0, 3, v0
	s_add_u32 s0, s68, s0
	v_and_b32_e32 v2, 4, v0
	s_addc_u32 s1, s69, 0
	v_lshlrev_b32_e32 v0, 2, v2
	v_lshl_add_u64 v[178:179], s[0:1], 0, v[0:1]
	v_readlane_b32 s0, v252, 31
	v_lshlrev_b32_e32 v0, 1, v2
	v_readlane_b32 s1, v252, 32
	v_mov_b32_e32 v17, v16
	v_mov_b32_e32 v18, v16
	v_mov_b32_e32 v19, v16
	v_mov_b32_e32 v20, v16
	v_mov_b32_e32 v21, v16
	v_mov_b32_e32 v22, v16
	v_mov_b32_e32 v23, v16
	v_mov_b32_e32 v24, v16
	v_mov_b32_e32 v25, v16
	v_mov_b32_e32 v26, v16
	v_mov_b32_e32 v27, v16
	v_mov_b32_e32 v28, v16
	v_mov_b32_e32 v29, v16
	v_mov_b32_e32 v30, v16
	v_mov_b32_e32 v31, v16
	v_mov_b32_e32 v177, v176
	v_lshl_add_u64 v[180:181], s[0:1], 0, v[0:1]
	s_branch .LBB0_1349
